# ATT2F units: one static s_setprio 1 for waves 4-7 for the duration of the unit (reset at the unit epilogue)
# baseline (speedup 1.0000x reference)
; template <bool DIFF, bool FIXED, bool F32SRC> ...
;     ...
;     float mrun = mref0, lrun = 0.f; f32x16 o[NDB];
; #pragma unroll
;     for (int db = 0; db < NDB; ++db) o[db] = f32x16{};
;     unsigned kgo[NCH], vgo[NCH];
; #pragma unroll
;     for (int i = 0; i < NCH; ++i) {
;         const int piece = w * NCH + i;
;         const int krow = DIFF ? (piece * 4 + (lane >> 4)) : (piece * 8 + (lane >> 3));
;         const int kcp = DIFF ? (lane & 15) : (lane & 7);
;         const int kch = kcp ^ (DIFF ? (krow & 15) : ((krow >> 1) & 7));
;         kgo[i] = (unsigned)(krow * PITCH + kch * 8);
;         const int p = piece * 64 + lane, st = p >> 5, key = 8 * (st / NDB) + ((p & 31) >> 2), dch = (st % NDB) * 4 + (p & 3);
;         vgo[i] = (unsigned)(key * PITCH + dch * 8);
;     }
;     ...
;     const int vlane = (4 * hi + ((lane & 15) >> 2)) * 64 + ((lane >> 4) & 1) * 32 + (lane & 3) * 8;
;     const int kswz = DIFF ? (q32 & 15) : ((q32 >> 1) & 7);
;     int koff[4];
; #pragma unroll
;     for (int ks = 0; ks < 4; ++ks) koff[ks] = q32 * RB + (((sub * 8 + 2 * ks + hi) ^ kswz) << 4);
;     int j = u.jhi, buf = 0;
;     ...
;                     const float base = -slopeL2 * dq - mrun;
; #pragma unroll
;                     for (int r = 0; r < 16; ++r) { const float c = (float)((r & 3) + 8 * (r >> 2)); a0[r] = slopeL2 * c + base; a1[r] = slopeL2 * (c + 32.f) + base; }
.LBB0_409:
	s_cmp_lt_i32 s61, 4
	v_mov_b32_e32 v17, 0
	s_cselect_b64 s[0:1], -1, 0
	v_lshlrev_b32_e32 v194, 2, v68
	s_cmp_lt_i32 s50, s24
	v_mov_b32_e32 v16, v17
	v_mov_b32_e32 v15, v17
	v_mov_b32_e32 v14, v17
	v_mov_b32_e32 v13, v17
	v_mov_b32_e32 v12, v17
	v_mov_b32_e32 v11, v17
	v_mov_b32_e32 v10, v17
	v_mov_b32_e32 v9, v17
	v_mov_b32_e32 v8, v17
	v_mov_b32_e32 v7, v17
	v_mov_b32_e32 v6, v17
	v_mov_b32_e32 v5, v17
	v_mov_b32_e32 v4, v17
	v_mov_b32_e32 v3, v17
	v_mov_b32_e32 v2, v17
	v_mov_b32_e32 v33, v17
	v_mov_b32_e32 v32, v17
	v_mov_b32_e32 v31, v17
	v_mov_b32_e32 v30, v17
	v_mov_b32_e32 v29, v17
	v_mov_b32_e32 v28, v17
	v_mov_b32_e32 v27, v17
	v_mov_b32_e32 v26, v17
	v_mov_b32_e32 v25, v17
	v_mov_b32_e32 v24, v17
	v_mov_b32_e32 v23, v17
	v_mov_b32_e32 v22, v17
	v_mov_b32_e32 v21, v17
	v_mov_b32_e32 v20, v17
	v_mov_b32_e32 v19, v17
	v_mov_b32_e32 v18, v17
	v_mov_b32_e32 v49, v17
	v_mov_b32_e32 v48, v17
	v_mov_b32_e32 v47, v17
	v_mov_b32_e32 v46, v17
	v_mov_b32_e32 v45, v17
	v_mov_b32_e32 v44, v17
	v_mov_b32_e32 v43, v17
	v_mov_b32_e32 v42, v17
	v_mov_b32_e32 v41, v17
	v_mov_b32_e32 v40, v17
	v_mov_b32_e32 v39, v17
	v_mov_b32_e32 v38, v17
	v_mov_b32_e32 v37, v17
	v_mov_b32_e32 v36, v17
	v_mov_b32_e32 v35, v17
	v_mov_b32_e32 v34, v17
	v_mov_b32_e32 v65, v17
	v_mov_b32_e32 v64, v17
	v_mov_b32_e32 v63, v17
	v_mov_b32_e32 v62, v17
	v_mov_b32_e32 v61, v17
	v_mov_b32_e32 v60, v17
	v_mov_b32_e32 v59, v17
	v_mov_b32_e32 v58, v17
	v_mov_b32_e32 v57, v17
	v_mov_b32_e32 v56, v17
	v_mov_b32_e32 v55, v17
	v_mov_b32_e32 v54, v17
	v_mov_b32_e32 v53, v17
	v_mov_b32_e32 v52, v17
	v_mov_b32_e32 v51, v17
	v_mov_b32_e32 v50, v17
	v_mov_b32_e32 v219, v17
	s_cbranch_scc1 .LBB0_462
	s_add_u32 s50, s74, s90
	s_addc_u32 s60, s75, 0
	v_readlane_b32 s12, v252, 55
	v_readlane_b32 s13, v252, 56
	s_add_u32 s63, s12, s90
	v_lshrrev_b32_e32 v2, 2, v67
	s_addc_u32 s64, s13, 0
	s_add_i32 s12, s16, s30
	v_and_or_b32 v2, v2, 3, v194
	v_lshlrev_b32_e32 v3, 1, v67
	v_and_b32_e32 v4, 15, v67
	s_lshl_b32 s13, s62, 3
	v_and_b32_e32 v3, 32, v3
	v_or_b32_e32 v5, s13, v68
	v_bitop3_b32 v6, s13, v4, v68 bitop3:0x36
	v_lshlrev_b32_e32 v2, 6, v2
	s_ashr_i32 s30, s12, 6
	s_mov_b32 s12, 2.0
	v_or3_b32 v225, v2, v3, v0
	v_mov_b32_e32 v0, v135
	s_mov_b32 s13, 0x40400000
	v_pk_mul_f32 v[162:163], v[0:1], s[12:13] op_sel_hi:[0,1]
	s_mov_b32 s12, 0x41000000
	s_mov_b32 s13, 0x41100000
	v_pk_mul_f32 v[164:165], v[0:1], s[12:13] op_sel_hi:[0,1]
	s_mov_b32 s12, 0x41200000
	s_mov_b32 s13, 0x41300000
	v_pk_mul_f32 v[166:167], v[0:1], s[12:13] op_sel_hi:[0,1]
	s_mov_b32 s12, 0x41800000
	s_mov_b32 s13, 0x41880000
	v_pk_mul_f32 v[168:169], v[0:1], s[12:13] op_sel_hi:[0,1]
	s_mov_b32 s12, 0x41900000
	s_mov_b32 s13, 0x41980000
	v_pk_mul_f32 v[170:171], v[0:1], s[12:13] op_sel_hi:[0,1]
	s_mov_b32 s12, 0x41c00000
	s_mov_b32 s13, 0x41c80000
	v_pk_mul_f32 v[172:173], v[0:1], s[12:13] op_sel_hi:[0,1]
	s_mov_b32 s12, 0x41d00000
	s_mov_b32 s13, 0x41d80000
	v_pk_mul_f32 v[174:175], v[0:1], s[12:13] op_sel_hi:[0,1]
	s_mov_b32 s12, 0x42680000
	s_mov_b32 s13, 0x426c0000
	v_pk_mul_f32 v[178:179], v[0:1], s[12:13] op_sel_hi:[0,1]
	s_mov_b32 s12, 0x42600000
	s_mov_b32 s13, 0x42640000
	v_pk_mul_f32 v[180:181], v[0:1], s[12:13] op_sel_hi:[0,1]
	s_mov_b32 s12, 0x42480000
	s_mov_b32 s13, 0x424c0000
	v_pk_mul_f32 v[182:183], v[0:1], s[12:13] op_sel_hi:[0,1]
	s_mov_b32 s12, 0x42400000
	s_mov_b32 s13, 0x42440000
	v_pk_mul_f32 v[184:185], v[0:1], s[12:13] op_sel_hi:[0,1]
	s_mov_b32 s12, 0x42280000
	s_mov_b32 s13, 0x422c0000
	v_pk_mul_f32 v[186:187], v[0:1], s[12:13] op_sel_hi:[0,1]
	s_mov_b32 s12, 0x42200000
	s_mov_b32 s13, 0x42240000
	v_pk_mul_f32 v[188:189], v[0:1], s[12:13] op_sel_hi:[0,1]
	s_mov_b32 s12, 0x42080000
	s_mov_b32 s13, 0x420c0000
	v_pk_mul_f32 v[190:191], v[0:1], s[12:13] op_sel_hi:[0,1]
	s_mov_b32 s12, 0x42000000
	s_mov_b32 s13, 0x42040000
	v_lshlrev_b32_e32 v221, 4, v6
	v_bitop3_b32 v6, v5, v4, 2 bitop3:0x36
	v_pk_mul_f32 v[192:193], v[0:1], s[12:13] op_sel_hi:[0,1]
	s_sub_i32 s12, s16, 64
	v_lshlrev_b32_e32 v222, 4, v6
	v_bitop3_b32 v6, v5, v4, 4 bitop3:0x36
	v_bitop3_b32 v4, v5, v4, 6 bitop3:0x36
	v_xor_b32_e32 v144, 0x80000000, v135
	v_mov_b32_e32 v219, 0
	v_add_u32_e32 v0, s12, v66
	v_lshlrev_b32_e32 v220, 8, v66
	v_lshlrev_b32_e32 v223, 4, v6
	v_lshlrev_b32_e32 v224, 4, v4
	s_sub_i32 s29, s30, s29
	v_mul_f32_e32 v134, 0, v135
	v_mov_b32_e32 v176, v144
	v_mov_b32_e32 v177, v144
	v_sub_u32_e32 v226, v0, v194
	s_add_i32 s25, s25, -1
	s_sub_i32 s12, s28, 64
	s_mov_b32 s28, 0
	v_mov_b32_e32 v50, 0
	v_mov_b32_e32 v51, v219
	v_mov_b32_e32 v52, v219
	v_mov_b32_e32 v53, v219
	v_mov_b32_e32 v54, v219
	v_mov_b32_e32 v55, v219
	v_mov_b32_e32 v56, v219
	v_mov_b32_e32 v57, v219
	v_mov_b32_e32 v58, v219
	v_mov_b32_e32 v59, v219
	v_mov_b32_e32 v60, v219
	v_mov_b32_e32 v61, v219
	v_mov_b32_e32 v62, v219
	v_mov_b32_e32 v63, v219
	v_mov_b32_e32 v64, v219
	v_mov_b32_e32 v65, v219
	v_mov_b32_e32 v34, 0
	v_mov_b32_e32 v35, v219
	v_mov_b32_e32 v36, v219
	v_mov_b32_e32 v37, v219
	v_mov_b32_e32 v38, v219
	v_mov_b32_e32 v39, v219
	v_mov_b32_e32 v40, v219
	v_mov_b32_e32 v41, v219
	v_mov_b32_e32 v42, v219
	v_mov_b32_e32 v43, v219
	v_mov_b32_e32 v44, v219
	v_mov_b32_e32 v45, v219
	v_mov_b32_e32 v46, v219
	v_mov_b32_e32 v47, v219
	v_mov_b32_e32 v48, v219
	v_mov_b32_e32 v49, v219
	v_mov_b32_e32 v18, 0
	v_mov_b32_e32 v19, v219
	v_mov_b32_e32 v20, v219
	v_mov_b32_e32 v21, v219
	v_mov_b32_e32 v22, v219
	v_mov_b32_e32 v23, v219
	v_mov_b32_e32 v24, v219
	v_mov_b32_e32 v25, v219
	v_mov_b32_e32 v26, v219
	v_mov_b32_e32 v27, v219
	v_mov_b32_e32 v28, v219
	v_mov_b32_e32 v29, v219
	v_mov_b32_e32 v30, v219
	v_mov_b32_e32 v31, v219
	v_mov_b32_e32 v32, v219
	v_mov_b32_e32 v33, v219
	v_mov_b32_e32 v2, 0
	v_mov_b32_e32 v3, v219
	v_mov_b32_e32 v4, v219
	v_mov_b32_e32 v5, v219
	v_mov_b32_e32 v6, v219
	v_mov_b32_e32 v7, v219
	v_mov_b32_e32 v8, v219
	v_mov_b32_e32 v9, v219
	v_mov_b32_e32 v10, v219
	v_mov_b32_e32 v11, v219
	v_mov_b32_e32 v12, v219
	v_mov_b32_e32 v13, v219
	v_mov_b32_e32 v14, v219
	v_mov_b32_e32 v15, v219
	v_mov_b32_e32 v16, v219
	v_mov_b32_e32 v17, v219
	s_cmp_ge_i32 s61, 2
	s_cbranch_scc0 .Lprio_skip
	s_setprio 1
.Lprio_skip:
	s_branch .LBB0_412

; #define LAS __attribute__((address_space(3)))
; __device__ __forceinline__ float x32_sum(float v) { float a = v, b = v; swap32(a, b); return a + b; }
; template <bool DIFF, bool FIXED, bool F32SRC> ...
;     ...
;     const float lt = x32_sum(lrun);
;     float sc = 1.f / lt;
;     if (DIFF) {
;         LAS f32x4* xch = (LAS f32x4*)lds;
;         if (wact && sub == 1) {
;             const float s1 = sc * lam;
; #pragma unroll
;             for (int db = 0; db < NDB; ++db)
; #pragma unroll
;                 for (int r4 = 0; r4 < 4; ++r4) xch[((qg * NDB + db) * 4 + r4) * 64 + lane] = (f32x4){o[db][4 * r4], o[db][4 * r4 + 1], o[db][4 * r4 + 2], o[db][4 * r4 + 3]} * s1;
;         }
.LBB0_462:
	s_setprio 0
	v_mov_b64_e32 v[146:147], 0xd1a
	v_mov_b64_e32 v[148:149], 0xd19
	v_mov_b64_e32 v[150:151], 0x204
	v_mov_b64_e32 v[152:153], 0x203
	v_mov_b64_e32 v[154:155], 0x200
	v_mov_b64_e32 v[156:157], 0x1ff
	v_mov_b64_e32 v[158:159], 0x810
	v_mov_b64_e32 v[160:161], 0x80f
	v_mov_b32_e32 v0, v219
	s_nop 1
	v_permlane32_swap_b32 v219, v0
	s_nop 1
	s_cmp_eq_u32 s62, 0
	v_add_f32_e32 v0, v219, v0
	v_div_scale_f32 v66, s[12:13], v0, v0, 1.0
	v_rcp_f32_e32 v67, v66
	v_div_scale_f32 v68, vcc, 1.0, v0, 1.0
	s_cselect_b64 s[12:13], -1, 0
	v_fma_f32 v69, -v66, v67, 1.0
	v_fmac_f32_e32 v67, v69, v67
	v_mul_f32_e32 v69, v68, v67
	v_fma_f32 v70, -v66, v69, v68
	v_fmac_f32_e32 v69, v70, v67
	v_fma_f32 v66, -v66, v69, v68
	s_xor_b64 s[16:17], s[0:1], -1
	v_div_fmas_f32 v66, v66, v67, v69
	s_or_b64 s[12:13], s[16:17], s[12:13]
	v_div_fixup_f32 v66, v66, v0, 1.0
	s_and_b64 vcc, exec, s[12:13]
	s_cbranch_vccnz .LBB0_464
	s_lshl_b32 s12, s61, 14
	v_mul_f32_e32 v0, s26, v66
	s_add_i32 s12, s12, 0
	v_pk_mul_f32 v[70:71], v[52:53], v[0:1] op_sel_hi:[1,0]
	v_pk_mul_f32 v[68:69], v[50:51], v[0:1] op_sel_hi:[1,0]
	v_lshl_add_u32 v67, v195, 4, s12
	ds_write_b128 v67, v[68:71]
	v_pk_mul_f32 v[70:71], v[56:57], v[0:1] op_sel_hi:[1,0]
	v_pk_mul_f32 v[68:69], v[54:55], v[0:1] op_sel_hi:[1,0]
	ds_write_b128 v67, v[68:71] offset:1024
	v_pk_mul_f32 v[70:71], v[60:61], v[0:1] op_sel_hi:[1,0]
	v_pk_mul_f32 v[68:69], v[58:59], v[0:1] op_sel_hi:[1,0]
	ds_write_b128 v67, v[68:71] offset:2048
	v_pk_mul_f32 v[70:71], v[64:65], v[0:1] op_sel_hi:[1,0]
	v_pk_mul_f32 v[68:69], v[62:63], v[0:1] op_sel_hi:[1,0]
	ds_write_b128 v67, v[68:71] offset:3072
	v_pk_mul_f32 v[70:71], v[36:37], v[0:1] op_sel_hi:[1,0]
	v_pk_mul_f32 v[68:69], v[34:35], v[0:1] op_sel_hi:[1,0]
	ds_write_b128 v67, v[68:71] offset:4096
	v_pk_mul_f32 v[70:71], v[40:41], v[0:1] op_sel_hi:[1,0]
	v_pk_mul_f32 v[68:69], v[38:39], v[0:1] op_sel_hi:[1,0]
	ds_write_b128 v67, v[68:71] offset:5120
	v_pk_mul_f32 v[70:71], v[44:45], v[0:1] op_sel_hi:[1,0]
	v_pk_mul_f32 v[68:69], v[42:43], v[0:1] op_sel_hi:[1,0]
	ds_write_b128 v67, v[68:71] offset:6144
	v_pk_mul_f32 v[70:71], v[48:49], v[0:1] op_sel_hi:[1,0]
	v_pk_mul_f32 v[68:69], v[46:47], v[0:1] op_sel_hi:[1,0]
	ds_write_b128 v67, v[68:71] offset:7168
	v_pk_mul_f32 v[70:71], v[20:21], v[0:1] op_sel_hi:[1,0]
	v_pk_mul_f32 v[68:69], v[18:19], v[0:1] op_sel_hi:[1,0]
	ds_write_b128 v67, v[68:71] offset:8192
	v_pk_mul_f32 v[70:71], v[24:25], v[0:1] op_sel_hi:[1,0]
	v_pk_mul_f32 v[68:69], v[22:23], v[0:1] op_sel_hi:[1,0]
	ds_write_b128 v67, v[68:71] offset:9216
	v_pk_mul_f32 v[70:71], v[28:29], v[0:1] op_sel_hi:[1,0]
	v_pk_mul_f32 v[68:69], v[26:27], v[0:1] op_sel_hi:[1,0]
	ds_write_b128 v67, v[68:71] offset:10240
	v_pk_mul_f32 v[70:71], v[32:33], v[0:1] op_sel_hi:[1,0]
	v_pk_mul_f32 v[68:69], v[30:31], v[0:1] op_sel_hi:[1,0]
	ds_write_b128 v67, v[68:71] offset:11264
	v_pk_mul_f32 v[70:71], v[4:5], v[0:1] op_sel_hi:[1,0]
	v_pk_mul_f32 v[68:69], v[2:3], v[0:1] op_sel_hi:[1,0]
	ds_write_b128 v67, v[68:71] offset:12288
	v_pk_mul_f32 v[70:71], v[8:9], v[0:1] op_sel_hi:[1,0]
	v_pk_mul_f32 v[68:69], v[6:7], v[0:1] op_sel_hi:[1,0]
	ds_write_b128 v67, v[68:71] offset:13312
	v_pk_mul_f32 v[70:71], v[12:13], v[0:1] op_sel_hi:[1,0]
	v_pk_mul_f32 v[68:69], v[10:11], v[0:1] op_sel_hi:[1,0]
	ds_write_b128 v67, v[68:71] offset:14336
	v_pk_mul_f32 v[70:71], v[16:17], v[0:1] op_sel_hi:[1,0]
	v_pk_mul_f32 v[68:69], v[14:15], v[0:1] op_sel_hi:[1,0]
	ds_write_b128 v67, v[68:71] offset:15360
